# e21: e20 (rotated dm_gen) with dm_gen relocated to the 224 idle WGs of P5's tail
# baseline (speedup 1.0000x reference)
.Le13_dm_entry:
	s_bitcmp1_b32 s90, 2
	s_cbranch_scc1 .LBB0_1373
	s_cmpk_gt_i32 s2, 0x20bf
	s_cbranch_scc1 .LBB0_1373
	s_mov_b32 s29, 0
	s_mul_i32 s4, s21, 0x2100
	s_mul_hi_i32 s5, s21, 0x2100
	s_add_u32 s4, s92, s4
	s_waitcnt vmcnt(0)
	v_mov_b32_e32 v2, 0
	v_mov_b32_e32 v3, 0
	s_addc_u32 s5, s93, s5
	s_movk_i32 s0, 0x210
	v_lshl_add_u64 v[2:3], s[4:5], 0, v[2:3]
	s_mov_b64 s[4:5], 0x11200000
	v_lshlrev_b32_e32 v1, 3, v0
	v_cmp_gt_u32_e64 s[0:1], s0, v0
	v_lshl_add_u64 v[2:3], v[2:3], 0, s[4:5]
	v_or_b32_e32 v6, 7, v1
	v_or_b32_e32 v7, 1, v1
	s_add_i32 s22, s21, 0x1000
	v_or_b32_e32 v8, 2, v1
	v_or_b32_e32 v9, 3, v1
	v_or_b32_e32 v10, 4, v1
	v_or_b32_e32 v11, 5, v1
	v_or_b32_e32 v12, 6, v1
	s_movk_i32 s23, 0xfff
	s_movk_i32 s24, 0x201
	s_movk_i32 s25, 0x200
	s_movk_i32 s26, 0x1001
	s_mov_b64 s[6:7], 0x2000
	s_mov_b64 s[8:9], 0x1ce000
	s_branch .LBB0_1338
.LBB0_1337:
	s_or_b64 exec, exec, s[10:11]
	s_add_i32 s29, s29, 1
	s_add_i32 s4, s21, 224
	s_add_i32 s22, s22, 224
	v_lshl_add_u64 v[2:3], v[2:3], 0, s[8:9]
	s_cmpk_gt_i32 s21, 0x1f1f
	s_mov_b32 s21, s4
	s_cbranch_scc1 .LBB0_1373
